# attention block: V s0 fragment reads issued right after the K d0 reads (before K d1), plus s_not mask inversions
# baseline (speedup 1.0000x reference)
.LBB0_542:
	s_cmp_gt_u32 s52, s51
	s_cbranch_scc1 .Lh1_skip
	s_mul_i32 s61, s25, 0x2200
	s_and_b32 s42, s52, 2
	s_mulk_i32 s42, 0x3400
	v_add_u32_e32 v0, s42, v160
	v_add_u32_e32 v242, s61, v161
	v_add_u32_e32 v163, 0xe000, v242
	v_add_u32_e32 v242, 0xd000, v242
	ds_read_b128 v[82:85], v0 offset:13312
	ds_read_b128 v[98:101], v0 offset:19968
	ds_read2_b64 v[238:241], v242 offset0:0 offset1:2
	ds_read2_b64 v[234:237], v163 offset0:32 offset1:34
	ds_read_b128 v[164:167], v0 offset:13344
	ds_read_b128 v[168:171], v0 offset:20000
	ds_read_b128 v[172:175], v0 offset:13376
	ds_read_b128 v[176:179], v0 offset:20032
	ds_read_b128 v[180:183], v0 offset:13408
	ds_read_b128 v[184:187], v0 offset:20064
	ds_read_b128 v[188:191], v0 offset:13440
	ds_read_b128 v[192:195], v0 offset:20096
	ds_read_b128 v[196:199], v0 offset:13472
	ds_read_b128 v[220:223], v0 offset:20128
	v_exp_f32_e32 v50, v50
	v_exp_f32_e32 v51, v51
	v_exp_f32_e32 v52, v52
	v_exp_f32_e32 v53, v53
	v_exp_f32_e32 v54, v54
	v_exp_f32_e32 v55, v55
	v_exp_f32_e32 v56, v56
	v_exp_f32_e32 v57, v57
	s_waitcnt lgkmcnt(13)
	v_mfma_f32_32x32x16_bf16 v[82:97], v[82:85], v[122:125], 0
	v_cvt_pk_bf16_f32 v224, v50, v51
	v_cvt_pk_bf16_f32 v225, v52, v53
	v_cvt_pk_bf16_f32 v226, v54, v55
	v_cvt_pk_bf16_f32 v227, v56, v57
	v_exp_f32_e32 v58, v58
	v_add_f32_e32 v200, v50, v51
	s_waitcnt lgkmcnt(12)
	v_mfma_f32_32x32x16_bf16 v[98:113], v[98:101], v[122:125], 0
	v_exp_f32_e32 v59, v59
	v_exp_f32_e32 v60, v60
	v_add_f32_e32 v201, v52, v53
	v_exp_f32_e32 v61, v61
	s_add_i32 s60, s52, 3
	s_cmp_lt_u32 s60, s48
	s_cselect_b64 s[58:59], -1, 0
	s_cmp_ge_u32 s60, s48
	s_cbranch_scc1 .Lp1a_546
	s_waitcnt vmcnt(0)
	v_lshl_add_u64 v[2:3], s[54:55], 0, v[154:155]
	v_add_co_u32_e32 v2, vcc, 0xbe09000, v2
	s_nop 1
	v_addc_co_u32_e32 v3, vcc, 0, v3, vcc
	global_load_dwordx4 v[2:5], v[2:3], off
	s_and_saveexec_b64 s[42:43], s[40:41]
	s_cbranch_execz .Lp1a_545
	v_lshl_add_u64 v[10:11], s[54:55], 0, v[152:153]
	v_add_co_u32_e32 v10, vcc, 0xbe09000, v10
	s_nop 1
	v_addc_co_u32_e32 v11, vcc, 0, v11, vcc
	global_load_dwordx4 v[10:13], v[10:11], off

.Lp1a_end:
	s_waitcnt lgkmcnt(9)
	v_mfma_f32_32x32x16_bf16 v[82:97], v[164:167], v[126:129], v[82:97]
	v_exp_f32_e32 v62, v62
	v_add_f32_e32 v200, v200, v54
	v_exp_f32_e32 v63, v63
	v_add_f32_e32 v201, v201, v55
	v_exp_f32_e32 v64, v64
	s_waitcnt lgkmcnt(8)
	v_mfma_f32_32x32x16_bf16 v[98:113], v[168:171], v[126:129], v[98:113]
	ds_read2_b64 v[164:167], v242 offset0:4 offset1:6
	ds_read2_b64 v[168:171], v163 offset0:36 offset1:38
	v_add_f32_e32 v200, v200, v56
	v_exp_f32_e32 v65, v65
	v_add_f32_e32 v201, v201, v57
	v_cvt_pk_bf16_f32 v228, v58, v59
	v_cvt_pk_bf16_f32 v229, v60, v61
	s_waitcnt lgkmcnt(13)
	v_mfma_f32_32x32x16_bf16 v[18:33], v[238:241], v[224:227], v[18:33]
	v_cvt_pk_bf16_f32 v230, v62, v63
	v_cvt_pk_bf16_f32 v231, v64, v65
	v_exp_f32_e32 v66, v66
	v_add_f32_e32 v200, v200, v58
	v_exp_f32_e32 v67, v67
	v_add_f32_e32 v201, v201, v59
	s_waitcnt lgkmcnt(12)
	v_mfma_f32_32x32x16_bf16 v[34:49], v[234:237], v[224:227], v[34:49]
	v_exp_f32_e32 v68, v68
	v_add_f32_e32 v200, v200, v60
	v_exp_f32_e32 v69, v69
	v_add_f32_e32 v201, v201, v61
	v_exp_f32_e32 v70, v70
	s_waitcnt lgkmcnt(9)
	v_mfma_f32_32x32x16_bf16 v[82:97], v[172:175], v[134:137], v[82:97]
	v_add_f32_e32 v200, v200, v62
	v_exp_f32_e32 v71, v71
	v_add_f32_e32 v201, v201, v63
	v_exp_f32_e32 v72, v72
	v_add_f32_e32 v200, v200, v64
	s_waitcnt lgkmcnt(8)
	v_mfma_f32_32x32x16_bf16 v[98:113], v[176:179], v[134:137], v[98:113]
	ds_read2_b64 v[172:175], v242 offset0:8 offset1:10
	ds_read2_b64 v[176:179], v163 offset0:40 offset1:42
	v_exp_f32_e32 v73, v73
	v_add_f32_e32 v201, v201, v65
	v_cvt_pk_bf16_f32 v224, v66, v67
	v_cvt_pk_bf16_f32 v225, v68, v69
	v_cvt_pk_bf16_f32 v226, v70, v71
	s_waitcnt lgkmcnt(3)
	v_mfma_f32_32x32x16_bf16 v[18:33], v[164:167], v[228:231], v[18:33]
	v_cvt_pk_bf16_f32 v227, v72, v73
	v_exp_f32_e32 v74, v74
	v_add_f32_e32 v200, v200, v66
	v_exp_f32_e32 v75, v75
	v_add_f32_e32 v201, v201, v67
	s_waitcnt lgkmcnt(2)
	v_mfma_f32_32x32x16_bf16 v[34:49], v[168:171], v[228:231], v[34:49]
	v_exp_f32_e32 v76, v76
	v_add_f32_e32 v200, v200, v68
	v_exp_f32_e32 v77, v77
	v_add_f32_e32 v201, v201, v69
	v_exp_f32_e32 v78, v78
	s_waitcnt lgkmcnt(9)
	v_mfma_f32_32x32x16_bf16 v[82:97], v[180:183], v[138:141], v[82:97]
	v_add_f32_e32 v200, v200, v70
	v_exp_f32_e32 v79, v79
	v_add_f32_e32 v201, v201, v71
	v_exp_f32_e32 v80, v80
	v_add_f32_e32 v200, v200, v72
	s_waitcnt lgkmcnt(8)
	v_mfma_f32_32x32x16_bf16 v[98:113], v[184:187], v[138:141], v[98:113]
	ds_read2_b64 v[180:183], v242 offset0:12 offset1:14
	ds_read2_b64 v[184:187], v163 offset0:44 offset1:46
	v_exp_f32_e32 v81, v81
	v_add_f32_e32 v201, v201, v73
	v_cvt_pk_bf16_f32 v228, v74, v75
	v_cvt_pk_bf16_f32 v229, v76, v77
	v_cvt_pk_bf16_f32 v230, v78, v79
	s_waitcnt lgkmcnt(3)
	v_mfma_f32_32x32x16_bf16 v[18:33], v[172:175], v[224:227], v[18:33]
	v_cvt_pk_bf16_f32 v231, v80, v81
	v_add_f32_e32 v200, v200, v74
	v_add_f32_e32 v201, v201, v75
	v_add_f32_e32 v200, v200, v76
	v_add_f32_e32 v201, v201, v77
	v_add_f32_e32 v200, v200, v78
	v_add_f32_e32 v201, v201, v79
	v_add_f32_e32 v200, v200, v80
	s_waitcnt lgkmcnt(2)
	v_mfma_f32_32x32x16_bf16 v[34:49], v[176:179], v[224:227], v[34:49]
	v_add_f32_e32 v201, v201, v81
	v_add_f32_e32 v200, v200, v201
	v_add_f32_e32 v162, v162, v200
	s_waitcnt lgkmcnt(9)
	v_mfma_f32_32x32x16_bf16 v[82:97], v[188:191], v[142:145], v[82:97]
	s_waitcnt lgkmcnt(8)
	v_mfma_f32_32x32x16_bf16 v[98:113], v[192:195], v[142:145], v[98:113]
	s_waitcnt lgkmcnt(7)
	v_mfma_f32_32x32x16_bf16 v[82:97], v[196:199], v[146:149], v[82:97]
	s_waitcnt lgkmcnt(6)
	v_mfma_f32_32x32x16_bf16 v[98:113], v[220:223], v[146:149], v[98:113]
	s_waitcnt lgkmcnt(0)
	s_not_b64 s[42:43], s[44:45]
	s_andn2_b64 vcc, exec, s[44:45]
	s_cbranch_vccnz .Lt1a_mid
	s_and_b32 s44, s53, 2
	s_mulk_i32 s44, 0x3400
	s_add_i32 s62, s44, 0
	v_add_u32_e32 v0, s62, v151
	s_waitcnt vmcnt(0)
	ds_write_b128 v0, v[118:121]
	s_and_saveexec_b64 s[44:45], s[40:41]
	v_add_u32_e32 v0, s62, v159
	ds_write_b128 v0, v[6:9]
	s_or_b64 exec, exec, s[44:45]

.LBB0_556:
	s_add_i32 s61, s25, 1
	s_cmp_lg_u32 s25, 2
	s_cselect_b32 s25, s61, 0
	s_andn2_b64 vcc, exec, s[44:45]
	s_waitcnt lgkmcnt(0)
	s_barrier
	s_cbranch_vccnz .LBB0_572
	s_cmp_ge_u32 s52, s51
	s_cbranch_scc1 .Lh2_skip
	s_andn2_b32 s62, 2, s52
	s_mulk_i32 s62, 0x3400
	v_add_u32_e32 v0, s62, v160
	s_mul_i32 s62, s25, 0x2200
	v_add_u32_e32 v242, s62, v161
	v_add_u32_e32 v163, 0xe000, v242
	v_add_u32_e32 v242, 0xd000, v242
	ds_read_b128 v[50:53], v0 offset:0
	ds_read_b128 v[66:69], v0 offset:6656
	ds_read2_b64 v[238:241], v242 offset0:0 offset1:2
	ds_read2_b64 v[234:237], v163 offset0:32 offset1:34
	ds_read_b128 v[164:167], v0 offset:32
	ds_read_b128 v[168:171], v0 offset:6688
	ds_read_b128 v[172:175], v0 offset:64
	ds_read_b128 v[176:179], v0 offset:6720
	ds_read_b128 v[180:183], v0 offset:96
	ds_read_b128 v[184:187], v0 offset:6752
	ds_read_b128 v[188:191], v0 offset:128
	ds_read_b128 v[192:195], v0 offset:6784
	ds_read_b128 v[196:199], v0 offset:160
	ds_read_b128 v[220:223], v0 offset:6816
	v_exp_f32_e32 v82, v82
	v_exp_f32_e32 v83, v83
	v_exp_f32_e32 v84, v84
	v_exp_f32_e32 v85, v85
	v_exp_f32_e32 v86, v86
	v_exp_f32_e32 v87, v87
	v_exp_f32_e32 v88, v88
	v_exp_f32_e32 v89, v89
	s_waitcnt lgkmcnt(13)
	v_mfma_f32_32x32x16_bf16 v[50:65], v[50:53], v[122:125], 0
	v_cvt_pk_bf16_f32 v224, v82, v83
	v_cvt_pk_bf16_f32 v225, v84, v85
	v_cvt_pk_bf16_f32 v226, v86, v87
	v_cvt_pk_bf16_f32 v227, v88, v89
	v_exp_f32_e32 v90, v90
	v_add_f32_e32 v200, v82, v83
	s_waitcnt lgkmcnt(12)
	v_mfma_f32_32x32x16_bf16 v[66:81], v[66:69], v[122:125], 0
	v_exp_f32_e32 v91, v91
	v_exp_f32_e32 v92, v92
	v_add_f32_e32 v201, v84, v85
	v_exp_f32_e32 v93, v93
	s_cmp_ge_u32 s52, s5
	s_cbranch_scc1 .Lp2a_561
	s_waitcnt vmcnt(0)
	v_lshl_add_u64 v[118:119], s[54:55], 0, v[154:155]
	v_add_co_u32_e32 v118, vcc, 0xbe0c000, v118
	s_nop 1
	v_addc_co_u32_e32 v119, vcc, 0, v119, vcc
	global_load_dwordx4 v[118:121], v[118:119], off
	s_and_saveexec_b64 s[44:45], s[40:41]
	s_cbranch_execz .Lp2a_560
	v_lshl_add_u64 v[6:7], s[54:55], 0, v[152:153]
	v_add_co_u32_e32 v6, vcc, 0xbe0c000, v6
	s_nop 1
	v_addc_co_u32_e32 v7, vcc, 0, v7, vcc
	global_load_dwordx4 v[6:9], v[6:7], off

.Lp2a_end:
	s_waitcnt lgkmcnt(9)
	v_mfma_f32_32x32x16_bf16 v[50:65], v[164:167], v[126:129], v[50:65]
	v_exp_f32_e32 v94, v94
	v_add_f32_e32 v200, v200, v86
	v_exp_f32_e32 v95, v95
	v_add_f32_e32 v201, v201, v87
	v_exp_f32_e32 v96, v96
	s_waitcnt lgkmcnt(8)
	v_mfma_f32_32x32x16_bf16 v[66:81], v[168:171], v[126:129], v[66:81]
	ds_read2_b64 v[164:167], v242 offset0:4 offset1:6
	ds_read2_b64 v[168:171], v163 offset0:36 offset1:38
	v_add_f32_e32 v200, v200, v88
	v_exp_f32_e32 v97, v97
	v_add_f32_e32 v201, v201, v89
	v_cvt_pk_bf16_f32 v228, v90, v91
	v_cvt_pk_bf16_f32 v229, v92, v93
	s_waitcnt lgkmcnt(13)
	v_mfma_f32_32x32x16_bf16 v[18:33], v[238:241], v[224:227], v[18:33]
	v_cvt_pk_bf16_f32 v230, v94, v95
	v_cvt_pk_bf16_f32 v231, v96, v97
	v_exp_f32_e32 v98, v98
	v_add_f32_e32 v200, v200, v90
	v_exp_f32_e32 v99, v99
	v_add_f32_e32 v201, v201, v91
	s_waitcnt lgkmcnt(12)
	v_mfma_f32_32x32x16_bf16 v[34:49], v[234:237], v[224:227], v[34:49]
	v_exp_f32_e32 v100, v100
	v_add_f32_e32 v200, v200, v92
	v_exp_f32_e32 v101, v101
	v_add_f32_e32 v201, v201, v93
	v_exp_f32_e32 v102, v102
	s_waitcnt lgkmcnt(9)
	v_mfma_f32_32x32x16_bf16 v[50:65], v[172:175], v[134:137], v[50:65]
	v_add_f32_e32 v200, v200, v94
	v_exp_f32_e32 v103, v103
	v_add_f32_e32 v201, v201, v95
	v_exp_f32_e32 v104, v104
	v_add_f32_e32 v200, v200, v96
	s_waitcnt lgkmcnt(8)
	v_mfma_f32_32x32x16_bf16 v[66:81], v[176:179], v[134:137], v[66:81]
	ds_read2_b64 v[172:175], v242 offset0:8 offset1:10
	ds_read2_b64 v[176:179], v163 offset0:40 offset1:42
	v_exp_f32_e32 v105, v105
	v_add_f32_e32 v201, v201, v97
	v_cvt_pk_bf16_f32 v224, v98, v99
	v_cvt_pk_bf16_f32 v225, v100, v101
	v_cvt_pk_bf16_f32 v226, v102, v103
	s_waitcnt lgkmcnt(3)
	v_mfma_f32_32x32x16_bf16 v[18:33], v[164:167], v[228:231], v[18:33]
	v_cvt_pk_bf16_f32 v227, v104, v105
	v_exp_f32_e32 v106, v106
	v_add_f32_e32 v200, v200, v98
	v_exp_f32_e32 v107, v107
	v_add_f32_e32 v201, v201, v99
	s_waitcnt lgkmcnt(2)
	v_mfma_f32_32x32x16_bf16 v[34:49], v[168:171], v[228:231], v[34:49]
	v_exp_f32_e32 v108, v108
	v_add_f32_e32 v200, v200, v100
	v_exp_f32_e32 v109, v109
	v_add_f32_e32 v201, v201, v101
	v_exp_f32_e32 v110, v110
	s_waitcnt lgkmcnt(9)
	v_mfma_f32_32x32x16_bf16 v[50:65], v[180:183], v[138:141], v[50:65]
	v_add_f32_e32 v200, v200, v102
	v_exp_f32_e32 v111, v111
	v_add_f32_e32 v201, v201, v103
	v_exp_f32_e32 v112, v112
	v_add_f32_e32 v200, v200, v104
	s_waitcnt lgkmcnt(8)
	v_mfma_f32_32x32x16_bf16 v[66:81], v[184:187], v[138:141], v[66:81]
	ds_read2_b64 v[180:183], v242 offset0:12 offset1:14
	ds_read2_b64 v[184:187], v163 offset0:44 offset1:46
	v_exp_f32_e32 v113, v113
	v_add_f32_e32 v201, v201, v105
	v_cvt_pk_bf16_f32 v228, v106, v107
	v_cvt_pk_bf16_f32 v229, v108, v109
	v_cvt_pk_bf16_f32 v230, v110, v111
	s_waitcnt lgkmcnt(3)
	v_mfma_f32_32x32x16_bf16 v[18:33], v[172:175], v[224:227], v[18:33]
	v_cvt_pk_bf16_f32 v231, v112, v113
	v_add_f32_e32 v200, v200, v106
	v_add_f32_e32 v201, v201, v107
	v_add_f32_e32 v200, v200, v108
	v_add_f32_e32 v201, v201, v109
	v_add_f32_e32 v200, v200, v110
	v_add_f32_e32 v201, v201, v111
	v_add_f32_e32 v200, v200, v112
	s_waitcnt lgkmcnt(2)
	v_mfma_f32_32x32x16_bf16 v[34:49], v[176:179], v[224:227], v[34:49]
	v_add_f32_e32 v201, v201, v113
	v_add_f32_e32 v200, v200, v201
	v_add_f32_e32 v162, v162, v200
	s_waitcnt lgkmcnt(9)
	v_mfma_f32_32x32x16_bf16 v[50:65], v[188:191], v[142:145], v[50:65]
	s_waitcnt lgkmcnt(8)
	v_mfma_f32_32x32x16_bf16 v[66:81], v[192:195], v[142:145], v[66:81]
	s_waitcnt lgkmcnt(7)
	v_mfma_f32_32x32x16_bf16 v[50:65], v[196:199], v[146:149], v[50:65]
	s_waitcnt lgkmcnt(6)
	v_mfma_f32_32x32x16_bf16 v[66:81], v[220:223], v[146:149], v[66:81]
	s_waitcnt lgkmcnt(0)
	s_mul_i32 s58, s25, 0x2200
	s_and_b64 vcc, exec, s[44:45]
	s_cbranch_vccnz .Lt2a_mid
	s_and_b32 s44, s60, 3
	s_mulk_i32 s44, 0x3400
	s_add_i32 s52, s44, 0
	v_add_u32_e32 v0, s52, v151
	s_waitcnt vmcnt(0)
	ds_write_b128 v0, v[2:5]
	s_and_saveexec_b64 s[44:45], s[40:41]
	v_add_u32_e32 v0, s52, v159
	ds_write_b128 v0, v[10:13]
	s_or_b64 exec, exec, s[44:45]
